# plus prologue GEMV inner loop software-pipelined (weight loads issued two iterations ahead)
# speedup vs baseline: 1.0182x; 1.0063x over previous
; __device__ __forceinline__ void phase_prologue(const Params& p, uchar* sm) {
;     ...
;         const float* wp = p.ada_w + (size_t)(w * 128) * NMODV + col;
; #pragma unroll 4
;         for (int k = 0; k < 128; ++k) { const float wv = wp[(size_t)k * NMODV];
; #pragma unroll
;             for (int b = 0; b < 16; ++b) acc[b] += sc[b * 1024 + w * 128 + k] * wv; }
.LBB0_32:
	v_ashrrev_i32_e32 v47, 31, v46
	v_lshl_add_u64 v[48:49], v[46:47], 2, v[44:45]
	s_mov_b64 s[2:3], 0
	v_mov_b32_e32 v47, v66
	v_mov_b32_e32 v50, 0
	v_mov_b32_e32 v51, v41
	v_mov_b32_e32 v52, 0
	v_mov_b32_e32 v53, v41
	v_mov_b32_e32 v54, 0
	v_mov_b32_e32 v55, v41
	v_mov_b32_e32 v56, 0
	v_mov_b32_e32 v57, v41
	v_mov_b32_e32 v58, 0
	v_mov_b32_e32 v59, v41
	v_mov_b32_e32 v60, 0
	v_mov_b32_e32 v61, v41
	v_mov_b32_e32 v62, 0
	v_mov_b32_e32 v63, v41
	v_mov_b32_e32 v64, 0
	v_mov_b32_e32 v65, v41
	v_lshl_add_u64 v[116:117], v[48:49], 0, s[2:3]
	v_lshl_add_u64 v[96:97], v[48:49], 0, s[2:3]
	v_add_co_u32_e64 v98, s[4:5], s9, v96
	s_nop 1
	v_addc_co_u32_e64 v99, s[4:5], 0, v97, s[4:5]
	global_load_dword v100, v[96:97], off
	v_add_co_u32_e64 v102, s[4:5], s11, v96
	s_nop 1
	v_addc_co_u32_e64 v103, s[4:5], 0, v97, s[4:5]
	v_add_co_u32_e64 v96, s[4:5], s12, v96
	s_nop 1
	v_addc_co_u32_e64 v97, s[4:5], 0, v97, s[4:5]
	global_load_dword v98, v[98:99], off
	global_load_dword v104, v[102:103], off
	global_load_dword v106, v[96:97], off
	s_mov_b32 s6, 0x60000
	v_add_co_u32_e64 v116, s[4:5], s6, v116
	s_nop 1
	v_addc_co_u32_e64 v117, s[4:5], 0, v117, s[4:5]
	v_lshl_add_u64 v[118:119], v[116:117], 0, s[2:3]
	v_add_co_u32_e64 v120, s[4:5], s9, v118
	s_nop 1
	v_addc_co_u32_e64 v121, s[4:5], 0, v119, s[4:5]
	global_load_dword v108, v[118:119], off
	v_add_co_u32_e64 v122, s[4:5], s11, v118
	s_nop 1
	v_addc_co_u32_e64 v123, s[4:5], 0, v119, s[4:5]
	v_add_co_u32_e64 v118, s[4:5], s12, v118
	s_nop 1
	v_addc_co_u32_e64 v119, s[4:5], 0, v119, s[4:5]
	global_load_dword v110, v[120:121], off
	global_load_dword v112, v[122:123], off
	global_load_dword v114, v[118:119], off
.LBB0_33:
	ds_read_b128 v[18:21], v47
	ds_read_b128 v[2:5], v47 offset:4096
	ds_read_b128 v[22:25], v47 offset:8192
	ds_read_b128 v[6:9], v47 offset:12288
	ds_read_b128 v[26:29], v47 offset:16384
	ds_read_b128 v[10:13], v47 offset:20480
	ds_read_b128 v[30:33], v47 offset:24576
	ds_read_b128 v[14:17], v47 offset:28672
	ds_read_b128 v[34:37], v47 offset:32768
	ds_read_b128 v[68:71], v47 offset:36864
	ds_read_b128 v[72:75], v47 offset:40960
	ds_read_b128 v[76:79], v47 offset:45056
	ds_read_b128 v[80:83], v47 offset:49152
	ds_read_b128 v[84:87], v47 offset:53248
	ds_read_b128 v[88:91], v47 offset:57344
	ds_read_b128 v[92:95], v47 offset:61440
	s_add_u32 s2, s2, 0x60000
	s_nop 0
	s_addc_u32 s3, s3, 0
	s_nop 0
	s_nop 0
	s_waitcnt lgkmcnt(14)
	v_mov_b32_e32 v96, v18
	v_mov_b32_e32 v97, v2
	v_mov_b32_e32 v2, v19
	v_mov_b32_e32 v18, v20
	v_mov_b32_e32 v19, v4
	v_mov_b32_e32 v4, v21
	s_waitcnt lgkmcnt(13)
	v_mov_b32_e32 v20, v22
	s_waitcnt lgkmcnt(12)
	v_mov_b32_e32 v21, v6
	v_mov_b32_e32 v6, v23
	v_mov_b32_e32 v22, v24
	v_mov_b32_e32 v23, v8
	v_mov_b32_e32 v8, v25
	s_waitcnt lgkmcnt(11)
	v_mov_b32_e32 v24, v26
	s_waitcnt lgkmcnt(10)
	v_mov_b32_e32 v25, v10
	v_mov_b32_e32 v10, v27
	v_mov_b32_e32 v26, v28
	v_mov_b32_e32 v27, v12
	v_mov_b32_e32 v12, v29
	s_waitcnt lgkmcnt(9)
	v_mov_b32_e32 v28, v30
	s_waitcnt lgkmcnt(8)
	v_mov_b32_e32 v29, v14
	v_mov_b32_e32 v14, v31
	v_mov_b32_e32 v30, v32
	v_mov_b32_e32 v31, v16
	v_mov_b32_e32 v16, v33
	s_waitcnt lgkmcnt(7)
	v_mov_b32_e32 v32, v34
	s_waitcnt lgkmcnt(6)
	v_mov_b32_e32 v33, v68
	v_mov_b32_e32 v68, v35
	v_mov_b32_e32 v34, v36
	v_mov_b32_e32 v35, v70
	v_mov_b32_e32 v70, v37
	s_waitcnt lgkmcnt(5)
	v_mov_b32_e32 v36, v72
	s_waitcnt lgkmcnt(4)
	v_mov_b32_e32 v37, v76
	v_mov_b32_e32 v76, v73
	v_mov_b32_e32 v72, v74
	v_mov_b32_e32 v73, v78
	v_mov_b32_e32 v78, v75
	s_waitcnt lgkmcnt(3)
	v_mov_b32_e32 v74, v80
	s_waitcnt lgkmcnt(2)
	v_mov_b32_e32 v75, v84
	v_mov_b32_e32 v84, v81
	v_mov_b32_e32 v80, v82
	v_mov_b32_e32 v81, v86
	v_mov_b32_e32 v86, v83
	s_waitcnt lgkmcnt(1)
	v_mov_b32_e32 v82, v88
	s_waitcnt lgkmcnt(0)
	v_mov_b32_e32 v83, v92
	v_mov_b32_e32 v92, v89
	v_mov_b32_e32 v88, v90
	v_mov_b32_e32 v89, v94
	v_mov_b32_e32 v94, v91
	v_add_u32_e32 v47, 16, v47
	s_waitcnt vmcnt(7)
	v_pk_fma_f32 v[52:53], v[100:101], v[96:97], v[52:53] op_sel_hi:[0,1,1]
	v_pk_fma_f32 v[20:21], v[100:101], v[20:21], v[54:55] op_sel_hi:[0,1,1]
	v_pk_fma_f32 v[24:25], v[100:101], v[24:25], v[56:57] op_sel_hi:[0,1,1]
	v_pk_fma_f32 v[28:29], v[100:101], v[28:29], v[58:59] op_sel_hi:[0,1,1]
	v_pk_fma_f32 v[32:33], v[100:101], v[32:33], v[60:61] op_sel_hi:[0,1,1]
	v_pk_fma_f32 v[36:37], v[100:101], v[36:37], v[62:63] op_sel_hi:[0,1,1]
	v_pk_fma_f32 v[54:55], v[100:101], v[74:75], v[64:65] op_sel_hi:[0,1,1]
	v_pk_fma_f32 v[50:51], v[100:101], v[82:83], v[50:51] op_sel_hi:[0,1,1]
	s_waitcnt vmcnt(6)
	v_pk_fma_f32 v[2:3], v[98:99], v[2:3], v[52:53] op_sel_hi:[0,1,1]
	v_pk_fma_f32 v[6:7], v[98:99], v[6:7], v[20:21] op_sel_hi:[0,1,1]
	v_pk_fma_f32 v[10:11], v[98:99], v[10:11], v[24:25] op_sel_hi:[0,1,1]
	v_pk_fma_f32 v[14:15], v[98:99], v[14:15], v[28:29] op_sel_hi:[0,1,1]
	v_pk_fma_f32 v[20:21], v[98:99], v[68:69], v[32:33] op_sel_hi:[0,1,1]
	v_pk_fma_f32 v[24:25], v[98:99], v[76:77], v[36:37] op_sel_hi:[0,1,1]
	v_pk_fma_f32 v[28:29], v[98:99], v[84:85], v[54:55] op_sel_hi:[0,1,1]
	v_pk_fma_f32 v[32:33], v[98:99], v[92:93], v[50:51] op_sel_hi:[0,1,1]
	s_waitcnt vmcnt(5)
	v_pk_fma_f32 v[2:3], v[104:105], v[18:19], v[2:3] op_sel_hi:[0,1,1]
	v_pk_fma_f32 v[6:7], v[104:105], v[22:23], v[6:7] op_sel_hi:[0,1,1]
	v_pk_fma_f32 v[10:11], v[104:105], v[26:27], v[10:11] op_sel_hi:[0,1,1]
	v_pk_fma_f32 v[14:15], v[104:105], v[30:31], v[14:15] op_sel_hi:[0,1,1]
	v_pk_fma_f32 v[18:19], v[104:105], v[34:35], v[20:21] op_sel_hi:[0,1,1]
	v_pk_fma_f32 v[20:21], v[104:105], v[72:73], v[24:25] op_sel_hi:[0,1,1]
	v_pk_fma_f32 v[22:23], v[104:105], v[80:81], v[28:29] op_sel_hi:[0,1,1]
	v_pk_fma_f32 v[24:25], v[104:105], v[88:89], v[32:33] op_sel_hi:[0,1,1]
	s_waitcnt vmcnt(4)
; __device__ __forceinline__ void phase_prologue(const Params& p, uchar* sm) {
;     ...
;         const float* wp = p.ada_w + (size_t)(w * 128) * NMODV + col;
; #pragma unroll 4
;         for (int k = 0; k < 128; ++k) { const float wv = wp[(size_t)k * NMODV];
; #pragma unroll
;             for (int b = 0; b < 16; ++b) acc[b] += sc[b * 1024 + w * 128 + k] * wv; }
	v_pk_fma_f32 v[52:53], v[106:107], v[4:5], v[2:3] op_sel_hi:[0,1,1]
	v_pk_fma_f32 v[54:55], v[106:107], v[8:9], v[6:7] op_sel_hi:[0,1,1]
	v_pk_fma_f32 v[56:57], v[106:107], v[12:13], v[10:11] op_sel_hi:[0,1,1]
	v_pk_fma_f32 v[58:59], v[106:107], v[16:17], v[14:15] op_sel_hi:[0,1,1]
	v_pk_fma_f32 v[60:61], v[106:107], v[70:71], v[18:19] op_sel_hi:[0,1,1]
	v_pk_fma_f32 v[62:63], v[106:107], v[78:79], v[20:21] op_sel_hi:[0,1,1]
	v_pk_fma_f32 v[64:65], v[106:107], v[86:87], v[22:23] op_sel_hi:[0,1,1]
	v_pk_fma_f32 v[50:51], v[106:107], v[94:95], v[24:25] op_sel_hi:[0,1,1]
	v_lshl_add_u64 v[96:97], v[116:117], 0, s[2:3]
	v_add_co_u32_e64 v98, s[4:5], s9, v96
	s_nop 1
	v_addc_co_u32_e64 v99, s[4:5], 0, v97, s[4:5]
	global_load_dword v100, v[96:97], off
	v_add_co_u32_e64 v102, s[4:5], s11, v96
	s_nop 1
	v_addc_co_u32_e64 v103, s[4:5], 0, v97, s[4:5]
	v_add_co_u32_e64 v96, s[4:5], s12, v96
	s_nop 1
	v_addc_co_u32_e64 v97, s[4:5], 0, v97, s[4:5]
	global_load_dword v98, v[98:99], off
	global_load_dword v104, v[102:103], off
	global_load_dword v106, v[96:97], off
	ds_read_b128 v[18:21], v47
	ds_read_b128 v[2:5], v47 offset:4096
	ds_read_b128 v[22:25], v47 offset:8192
	ds_read_b128 v[6:9], v47 offset:12288
	ds_read_b128 v[26:29], v47 offset:16384
	ds_read_b128 v[10:13], v47 offset:20480
	ds_read_b128 v[30:33], v47 offset:24576
	ds_read_b128 v[14:17], v47 offset:28672
	ds_read_b128 v[34:37], v47 offset:32768
	ds_read_b128 v[68:71], v47 offset:36864
	ds_read_b128 v[72:75], v47 offset:40960
	ds_read_b128 v[76:79], v47 offset:45056
	ds_read_b128 v[80:83], v47 offset:49152
	ds_read_b128 v[84:87], v47 offset:53248
	ds_read_b128 v[88:91], v47 offset:57344
	ds_read_b128 v[92:95], v47 offset:61440
	s_add_u32 s2, s2, 0x60000
	s_nop 0
	s_addc_u32 s3, s3, 0
	s_nop 0
	s_nop 0
	s_waitcnt lgkmcnt(14)
	v_mov_b32_e32 v96, v18
	v_mov_b32_e32 v97, v2
	v_mov_b32_e32 v2, v19
	v_mov_b32_e32 v18, v20
	v_mov_b32_e32 v19, v4
	v_mov_b32_e32 v4, v21
	s_waitcnt lgkmcnt(13)
	v_mov_b32_e32 v20, v22
	s_waitcnt lgkmcnt(12)
	v_mov_b32_e32 v21, v6
	v_mov_b32_e32 v6, v23
	v_mov_b32_e32 v22, v24
	v_mov_b32_e32 v23, v8
	v_mov_b32_e32 v8, v25
	s_waitcnt lgkmcnt(11)
	v_mov_b32_e32 v24, v26
	s_waitcnt lgkmcnt(10)
	v_mov_b32_e32 v25, v10
	v_mov_b32_e32 v10, v27
	v_mov_b32_e32 v26, v28
	v_mov_b32_e32 v27, v12
	v_mov_b32_e32 v12, v29
	s_waitcnt lgkmcnt(9)
	v_mov_b32_e32 v28, v30
	s_waitcnt lgkmcnt(8)
	v_mov_b32_e32 v29, v14
	v_mov_b32_e32 v14, v31
	v_mov_b32_e32 v30, v32
	v_mov_b32_e32 v31, v16
	v_mov_b32_e32 v16, v33
	s_waitcnt lgkmcnt(7)
	v_mov_b32_e32 v32, v34
	s_waitcnt lgkmcnt(6)
	v_mov_b32_e32 v33, v68
	v_mov_b32_e32 v68, v35
	v_mov_b32_e32 v34, v36
	v_mov_b32_e32 v35, v70
	v_mov_b32_e32 v70, v37
	s_waitcnt lgkmcnt(5)
	v_mov_b32_e32 v36, v72
	s_waitcnt lgkmcnt(4)
	v_mov_b32_e32 v37, v76
	v_mov_b32_e32 v76, v73
	v_mov_b32_e32 v72, v74
	v_mov_b32_e32 v73, v78
	v_mov_b32_e32 v78, v75
	s_waitcnt lgkmcnt(3)
	v_mov_b32_e32 v74, v80
	s_waitcnt lgkmcnt(2)
	v_mov_b32_e32 v75, v84
	v_mov_b32_e32 v84, v81
	v_mov_b32_e32 v80, v82
	v_mov_b32_e32 v81, v86
	v_mov_b32_e32 v86, v83
	s_waitcnt lgkmcnt(1)
	v_mov_b32_e32 v82, v88
	s_waitcnt lgkmcnt(0)
	v_mov_b32_e32 v83, v92
	v_mov_b32_e32 v92, v89
	v_mov_b32_e32 v88, v90
	v_mov_b32_e32 v89, v94
	v_mov_b32_e32 v94, v91
	v_add_u32_e32 v47, 16, v47
	s_waitcnt vmcnt(7)
	v_pk_fma_f32 v[52:53], v[108:109], v[96:97], v[52:53] op_sel_hi:[0,1,1]
	v_pk_fma_f32 v[20:21], v[108:109], v[20:21], v[54:55] op_sel_hi:[0,1,1]
	v_pk_fma_f32 v[24:25], v[108:109], v[24:25], v[56:57] op_sel_hi:[0,1,1]
	v_pk_fma_f32 v[28:29], v[108:109], v[28:29], v[58:59] op_sel_hi:[0,1,1]
	v_pk_fma_f32 v[32:33], v[108:109], v[32:33], v[60:61] op_sel_hi:[0,1,1]
	v_pk_fma_f32 v[36:37], v[108:109], v[36:37], v[62:63] op_sel_hi:[0,1,1]
	v_pk_fma_f32 v[54:55], v[108:109], v[74:75], v[64:65] op_sel_hi:[0,1,1]
	v_pk_fma_f32 v[50:51], v[108:109], v[82:83], v[50:51] op_sel_hi:[0,1,1]
	s_waitcnt vmcnt(6)
	v_pk_fma_f32 v[2:3], v[110:111], v[2:3], v[52:53] op_sel_hi:[0,1,1]
	v_pk_fma_f32 v[6:7], v[110:111], v[6:7], v[20:21] op_sel_hi:[0,1,1]
	v_pk_fma_f32 v[10:11], v[110:111], v[10:11], v[24:25] op_sel_hi:[0,1,1]
	v_pk_fma_f32 v[14:15], v[110:111], v[14:15], v[28:29] op_sel_hi:[0,1,1]
	v_pk_fma_f32 v[20:21], v[110:111], v[68:69], v[32:33] op_sel_hi:[0,1,1]
	v_pk_fma_f32 v[24:25], v[110:111], v[76:77], v[36:37] op_sel_hi:[0,1,1]
	v_pk_fma_f32 v[28:29], v[110:111], v[84:85], v[54:55] op_sel_hi:[0,1,1]
	v_pk_fma_f32 v[32:33], v[110:111], v[92:93], v[50:51] op_sel_hi:[0,1,1]
	s_waitcnt vmcnt(5)
	v_pk_fma_f32 v[2:3], v[112:113], v[18:19], v[2:3] op_sel_hi:[0,1,1]
	v_pk_fma_f32 v[6:7], v[112:113], v[22:23], v[6:7] op_sel_hi:[0,1,1]
	v_pk_fma_f32 v[10:11], v[112:113], v[26:27], v[10:11] op_sel_hi:[0,1,1]
	v_pk_fma_f32 v[14:15], v[112:113], v[30:31], v[14:15] op_sel_hi:[0,1,1]
	v_pk_fma_f32 v[18:19], v[112:113], v[34:35], v[20:21] op_sel_hi:[0,1,1]
	v_pk_fma_f32 v[20:21], v[112:113], v[72:73], v[24:25] op_sel_hi:[0,1,1]
	v_pk_fma_f32 v[22:23], v[112:113], v[80:81], v[28:29] op_sel_hi:[0,1,1]
	v_pk_fma_f32 v[24:25], v[112:113], v[88:89], v[32:33] op_sel_hi:[0,1,1]
	s_waitcnt vmcnt(4)
	v_pk_fma_f32 v[52:53], v[114:115], v[4:5], v[2:3] op_sel_hi:[0,1,1]
	v_pk_fma_f32 v[54:55], v[114:115], v[8:9], v[6:7] op_sel_hi:[0,1,1]
	v_pk_fma_f32 v[56:57], v[114:115], v[12:13], v[10:11] op_sel_hi:[0,1,1]
	v_pk_fma_f32 v[58:59], v[114:115], v[16:17], v[14:15] op_sel_hi:[0,1,1]
	v_pk_fma_f32 v[60:61], v[114:115], v[70:71], v[18:19] op_sel_hi:[0,1,1]
	v_pk_fma_f32 v[62:63], v[114:115], v[78:79], v[20:21] op_sel_hi:[0,1,1]
	v_pk_fma_f32 v[64:65], v[114:115], v[86:87], v[22:23] op_sel_hi:[0,1,1]
	v_pk_fma_f32 v[50:51], v[114:115], v[94:95], v[24:25] op_sel_hi:[0,1,1]
	v_lshl_add_u64 v[118:119], v[116:117], 0, s[2:3]
	v_add_co_u32_e64 v120, s[4:5], s9, v118
	s_nop 1
	v_addc_co_u32_e64 v121, s[4:5], 0, v119, s[4:5]
	global_load_dword v108, v[118:119], off
	v_add_co_u32_e64 v122, s[4:5], s11, v118
	s_nop 1
	v_addc_co_u32_e64 v123, s[4:5], 0, v119, s[4:5]
	v_add_co_u32_e64 v118, s[4:5], s12, v118
	s_nop 1
	v_addc_co_u32_e64 v119, s[4:5], 0, v119, s[4:5]
	global_load_dword v110, v[120:121], off
	global_load_dword v112, v[122:123], off
	global_load_dword v114, v[118:119], off
	s_cmp_lg_u32 s2, 0xb40000
	s_cbranch_scc1 .LBB0_33
; __device__ __forceinline__ void phase_prologue(const Params& p, uchar* sm) {
;     ...
;         const float* wp = p.ada_w + (size_t)(w * 128) * NMODV + col;
; #pragma unroll 4
;         for (int k = 0; k < 128; ++k) { const float wv = wp[(size_t)k * NMODV];
; #pragma unroll
;             for (int b = 0; b < 16; ++b) acc[b] += sc[b * 1024 + w * 128 + k] * wv; }
	ds_read_b128 v[18:21], v47
	ds_read_b128 v[2:5], v47 offset:4096
	ds_read_b128 v[22:25], v47 offset:8192
	ds_read_b128 v[6:9], v47 offset:12288
	ds_read_b128 v[26:29], v47 offset:16384
	ds_read_b128 v[10:13], v47 offset:20480
	ds_read_b128 v[30:33], v47 offset:24576
	ds_read_b128 v[14:17], v47 offset:28672
	ds_read_b128 v[34:37], v47 offset:32768
	ds_read_b128 v[68:71], v47 offset:36864
	ds_read_b128 v[72:75], v47 offset:40960
	ds_read_b128 v[76:79], v47 offset:45056
	ds_read_b128 v[80:83], v47 offset:49152
	ds_read_b128 v[84:87], v47 offset:53248
	ds_read_b128 v[88:91], v47 offset:57344
	ds_read_b128 v[92:95], v47 offset:61440
	s_add_u32 s2, s2, 0x60000
	s_nop 0
	s_addc_u32 s3, s3, 0
	s_nop 0
	s_nop 0
	s_waitcnt lgkmcnt(14)
	v_mov_b32_e32 v96, v18
	v_mov_b32_e32 v97, v2
	v_mov_b32_e32 v2, v19
	v_mov_b32_e32 v18, v20
	v_mov_b32_e32 v19, v4
	v_mov_b32_e32 v4, v21
	s_waitcnt lgkmcnt(13)
	v_mov_b32_e32 v20, v22
	s_waitcnt lgkmcnt(12)
	v_mov_b32_e32 v21, v6
	v_mov_b32_e32 v6, v23
	v_mov_b32_e32 v22, v24
	v_mov_b32_e32 v23, v8
	v_mov_b32_e32 v8, v25
	s_waitcnt lgkmcnt(11)
	v_mov_b32_e32 v24, v26
	s_waitcnt lgkmcnt(10)
	v_mov_b32_e32 v25, v10
	v_mov_b32_e32 v10, v27
	v_mov_b32_e32 v26, v28
	v_mov_b32_e32 v27, v12
	v_mov_b32_e32 v12, v29
	s_waitcnt lgkmcnt(9)
	v_mov_b32_e32 v28, v30
	s_waitcnt lgkmcnt(8)
	v_mov_b32_e32 v29, v14
	v_mov_b32_e32 v14, v31
	v_mov_b32_e32 v30, v32
	v_mov_b32_e32 v31, v16
	v_mov_b32_e32 v16, v33
	s_waitcnt lgkmcnt(7)
	v_mov_b32_e32 v32, v34
	s_waitcnt lgkmcnt(6)
	v_mov_b32_e32 v33, v68
	v_mov_b32_e32 v68, v35
	v_mov_b32_e32 v34, v36
	v_mov_b32_e32 v35, v70
	v_mov_b32_e32 v70, v37
	s_waitcnt lgkmcnt(5)
	v_mov_b32_e32 v36, v72
	s_waitcnt lgkmcnt(4)
	v_mov_b32_e32 v37, v76
	v_mov_b32_e32 v76, v73
	v_mov_b32_e32 v72, v74
	v_mov_b32_e32 v73, v78
	v_mov_b32_e32 v78, v75
	s_waitcnt lgkmcnt(3)
	v_mov_b32_e32 v74, v80
	s_waitcnt lgkmcnt(2)
	v_mov_b32_e32 v75, v84
	v_mov_b32_e32 v84, v81
	v_mov_b32_e32 v80, v82
	v_mov_b32_e32 v81, v86
	v_mov_b32_e32 v86, v83
	s_waitcnt lgkmcnt(1)
	v_mov_b32_e32 v82, v88
	s_waitcnt lgkmcnt(0)
	v_mov_b32_e32 v83, v92
	v_mov_b32_e32 v92, v89
	v_mov_b32_e32 v88, v90
	v_mov_b32_e32 v89, v94
	v_mov_b32_e32 v94, v91
	v_add_u32_e32 v47, 16, v47
	s_waitcnt vmcnt(7)
	v_pk_fma_f32 v[52:53], v[100:101], v[96:97], v[52:53] op_sel_hi:[0,1,1]
	v_pk_fma_f32 v[20:21], v[100:101], v[20:21], v[54:55] op_sel_hi:[0,1,1]
	v_pk_fma_f32 v[24:25], v[100:101], v[24:25], v[56:57] op_sel_hi:[0,1,1]
	v_pk_fma_f32 v[28:29], v[100:101], v[28:29], v[58:59] op_sel_hi:[0,1,1]
	v_pk_fma_f32 v[32:33], v[100:101], v[32:33], v[60:61] op_sel_hi:[0,1,1]
	v_pk_fma_f32 v[36:37], v[100:101], v[36:37], v[62:63] op_sel_hi:[0,1,1]
	v_pk_fma_f32 v[54:55], v[100:101], v[74:75], v[64:65] op_sel_hi:[0,1,1]
	v_pk_fma_f32 v[50:51], v[100:101], v[82:83], v[50:51] op_sel_hi:[0,1,1]
	s_waitcnt vmcnt(6)
	v_pk_fma_f32 v[2:3], v[98:99], v[2:3], v[52:53] op_sel_hi:[0,1,1]
	v_pk_fma_f32 v[6:7], v[98:99], v[6:7], v[20:21] op_sel_hi:[0,1,1]
	v_pk_fma_f32 v[10:11], v[98:99], v[10:11], v[24:25] op_sel_hi:[0,1,1]
	v_pk_fma_f32 v[14:15], v[98:99], v[14:15], v[28:29] op_sel_hi:[0,1,1]
	v_pk_fma_f32 v[20:21], v[98:99], v[68:69], v[32:33] op_sel_hi:[0,1,1]
	v_pk_fma_f32 v[24:25], v[98:99], v[76:77], v[36:37] op_sel_hi:[0,1,1]
	v_pk_fma_f32 v[28:29], v[98:99], v[84:85], v[54:55] op_sel_hi:[0,1,1]
	v_pk_fma_f32 v[32:33], v[98:99], v[92:93], v[50:51] op_sel_hi:[0,1,1]
	s_waitcnt vmcnt(5)
	v_pk_fma_f32 v[2:3], v[104:105], v[18:19], v[2:3] op_sel_hi:[0,1,1]
	v_pk_fma_f32 v[6:7], v[104:105], v[22:23], v[6:7] op_sel_hi:[0,1,1]
	v_pk_fma_f32 v[10:11], v[104:105], v[26:27], v[10:11] op_sel_hi:[0,1,1]
	v_pk_fma_f32 v[14:15], v[104:105], v[30:31], v[14:15] op_sel_hi:[0,1,1]
	v_pk_fma_f32 v[18:19], v[104:105], v[34:35], v[20:21] op_sel_hi:[0,1,1]
	v_pk_fma_f32 v[20:21], v[104:105], v[72:73], v[24:25] op_sel_hi:[0,1,1]
	v_pk_fma_f32 v[22:23], v[104:105], v[80:81], v[28:29] op_sel_hi:[0,1,1]
	v_pk_fma_f32 v[24:25], v[104:105], v[88:89], v[32:33] op_sel_hi:[0,1,1]
	s_waitcnt vmcnt(4)
	v_pk_fma_f32 v[52:53], v[106:107], v[4:5], v[2:3] op_sel_hi:[0,1,1]
	v_pk_fma_f32 v[54:55], v[106:107], v[8:9], v[6:7] op_sel_hi:[0,1,1]
	v_pk_fma_f32 v[56:57], v[106:107], v[12:13], v[10:11] op_sel_hi:[0,1,1]
	v_pk_fma_f32 v[58:59], v[106:107], v[16:17], v[14:15] op_sel_hi:[0,1,1]
	v_pk_fma_f32 v[60:61], v[106:107], v[70:71], v[18:19] op_sel_hi:[0,1,1]
	v_pk_fma_f32 v[62:63], v[106:107], v[78:79], v[20:21] op_sel_hi:[0,1,1]
	v_pk_fma_f32 v[64:65], v[106:107], v[86:87], v[22:23] op_sel_hi:[0,1,1]
	v_pk_fma_f32 v[50:51], v[106:107], v[94:95], v[24:25] op_sel_hi:[0,1,1]
	ds_read_b128 v[18:21], v47
	ds_read_b128 v[2:5], v47 offset:4096
	ds_read_b128 v[22:25], v47 offset:8192
	ds_read_b128 v[6:9], v47 offset:12288
	ds_read_b128 v[26:29], v47 offset:16384
	ds_read_b128 v[10:13], v47 offset:20480
	ds_read_b128 v[30:33], v47 offset:24576
	ds_read_b128 v[14:17], v47 offset:28672
	ds_read_b128 v[34:37], v47 offset:32768
	ds_read_b128 v[68:71], v47 offset:36864
	ds_read_b128 v[72:75], v47 offset:40960
	ds_read_b128 v[76:79], v47 offset:45056
	ds_read_b128 v[80:83], v47 offset:49152
	ds_read_b128 v[84:87], v47 offset:53248
	ds_read_b128 v[88:91], v47 offset:57344
	ds_read_b128 v[92:95], v47 offset:61440
	s_add_u32 s2, s2, 0x60000
	s_nop 0
	s_addc_u32 s3, s3, 0
	s_nop 0
	s_nop 0
	s_waitcnt lgkmcnt(14)
; __device__ __forceinline__ void phase_prologue(const Params& p, uchar* sm) {
;     ...
;         const float* wp = p.ada_w + (size_t)(w * 128) * NMODV + col;
; #pragma unroll 4
;         for (int k = 0; k < 128; ++k) { const float wv = wp[(size_t)k * NMODV];
; #pragma unroll
;             for (int b = 0; b < 16; ++b) acc[b] += sc[b * 1024 + w * 128 + k] * wv; }
; #pragma unroll
;         for (int b = 0; b < 16; ++b) red[(w * 16 + b) * 64 + lane] = acc[b];
;         __syncthreads();
;         for (int o = tid; o < 1024; o += 512) { const int b = o >> 6, cl = o & 63; float s = p.ada_b[item * 64 + cl];
	v_mov_b32_e32 v96, v18
	v_mov_b32_e32 v97, v2
	v_mov_b32_e32 v2, v19
	v_mov_b32_e32 v18, v20
	v_mov_b32_e32 v19, v4
	v_mov_b32_e32 v4, v21
	s_waitcnt lgkmcnt(13)
	v_mov_b32_e32 v20, v22
	s_waitcnt lgkmcnt(12)
	v_mov_b32_e32 v21, v6
	v_mov_b32_e32 v6, v23
	v_mov_b32_e32 v22, v24
	v_mov_b32_e32 v23, v8
	v_mov_b32_e32 v8, v25
	s_waitcnt lgkmcnt(11)
	v_mov_b32_e32 v24, v26
	s_waitcnt lgkmcnt(10)
	v_mov_b32_e32 v25, v10
	v_mov_b32_e32 v10, v27
	v_mov_b32_e32 v26, v28
	v_mov_b32_e32 v27, v12
	v_mov_b32_e32 v12, v29
	s_waitcnt lgkmcnt(9)
	v_mov_b32_e32 v28, v30
	s_waitcnt lgkmcnt(8)
	v_mov_b32_e32 v29, v14
	v_mov_b32_e32 v14, v31
	v_mov_b32_e32 v30, v32
	v_mov_b32_e32 v31, v16
	v_mov_b32_e32 v16, v33
	s_waitcnt lgkmcnt(7)
	v_mov_b32_e32 v32, v34
	s_waitcnt lgkmcnt(6)
	v_mov_b32_e32 v33, v68
	v_mov_b32_e32 v68, v35
	v_mov_b32_e32 v34, v36
	v_mov_b32_e32 v35, v70
	v_mov_b32_e32 v70, v37
	s_waitcnt lgkmcnt(5)
	v_mov_b32_e32 v36, v72
	s_waitcnt lgkmcnt(4)
	v_mov_b32_e32 v37, v76
	v_mov_b32_e32 v76, v73
	v_mov_b32_e32 v72, v74
	v_mov_b32_e32 v73, v78
	v_mov_b32_e32 v78, v75
	s_waitcnt lgkmcnt(3)
	v_mov_b32_e32 v74, v80
	s_waitcnt lgkmcnt(2)
	v_mov_b32_e32 v75, v84
	v_mov_b32_e32 v84, v81
	v_mov_b32_e32 v80, v82
	v_mov_b32_e32 v81, v86
	v_mov_b32_e32 v86, v83
	s_waitcnt lgkmcnt(1)
	v_mov_b32_e32 v82, v88
	s_waitcnt lgkmcnt(0)
	v_mov_b32_e32 v83, v92
	v_mov_b32_e32 v92, v89
	v_mov_b32_e32 v88, v90
	v_mov_b32_e32 v89, v94
	v_mov_b32_e32 v94, v91
	v_add_u32_e32 v47, 16, v47
	s_waitcnt vmcnt(3)
	v_pk_fma_f32 v[52:53], v[108:109], v[96:97], v[52:53] op_sel_hi:[0,1,1]
	v_pk_fma_f32 v[20:21], v[108:109], v[20:21], v[54:55] op_sel_hi:[0,1,1]
	v_pk_fma_f32 v[24:25], v[108:109], v[24:25], v[56:57] op_sel_hi:[0,1,1]
	v_pk_fma_f32 v[28:29], v[108:109], v[28:29], v[58:59] op_sel_hi:[0,1,1]
	v_pk_fma_f32 v[32:33], v[108:109], v[32:33], v[60:61] op_sel_hi:[0,1,1]
	v_pk_fma_f32 v[36:37], v[108:109], v[36:37], v[62:63] op_sel_hi:[0,1,1]
	v_pk_fma_f32 v[54:55], v[108:109], v[74:75], v[64:65] op_sel_hi:[0,1,1]
	v_pk_fma_f32 v[50:51], v[108:109], v[82:83], v[50:51] op_sel_hi:[0,1,1]
	s_waitcnt vmcnt(2)
	v_pk_fma_f32 v[2:3], v[110:111], v[2:3], v[52:53] op_sel_hi:[0,1,1]
	v_pk_fma_f32 v[6:7], v[110:111], v[6:7], v[20:21] op_sel_hi:[0,1,1]
	v_pk_fma_f32 v[10:11], v[110:111], v[10:11], v[24:25] op_sel_hi:[0,1,1]
	v_pk_fma_f32 v[14:15], v[110:111], v[14:15], v[28:29] op_sel_hi:[0,1,1]
	v_pk_fma_f32 v[20:21], v[110:111], v[68:69], v[32:33] op_sel_hi:[0,1,1]
	v_pk_fma_f32 v[24:25], v[110:111], v[76:77], v[36:37] op_sel_hi:[0,1,1]
	v_pk_fma_f32 v[28:29], v[110:111], v[84:85], v[54:55] op_sel_hi:[0,1,1]
	v_pk_fma_f32 v[32:33], v[110:111], v[92:93], v[50:51] op_sel_hi:[0,1,1]
	s_waitcnt vmcnt(1)
	v_pk_fma_f32 v[2:3], v[112:113], v[18:19], v[2:3] op_sel_hi:[0,1,1]
	v_pk_fma_f32 v[6:7], v[112:113], v[22:23], v[6:7] op_sel_hi:[0,1,1]
	v_pk_fma_f32 v[10:11], v[112:113], v[26:27], v[10:11] op_sel_hi:[0,1,1]
	v_pk_fma_f32 v[14:15], v[112:113], v[30:31], v[14:15] op_sel_hi:[0,1,1]
	v_pk_fma_f32 v[18:19], v[112:113], v[34:35], v[20:21] op_sel_hi:[0,1,1]
	v_pk_fma_f32 v[20:21], v[112:113], v[72:73], v[24:25] op_sel_hi:[0,1,1]
	v_pk_fma_f32 v[22:23], v[112:113], v[80:81], v[28:29] op_sel_hi:[0,1,1]
	v_pk_fma_f32 v[24:25], v[112:113], v[88:89], v[32:33] op_sel_hi:[0,1,1]
	s_waitcnt vmcnt(0)
	v_pk_fma_f32 v[52:53], v[114:115], v[4:5], v[2:3] op_sel_hi:[0,1,1]
	v_pk_fma_f32 v[54:55], v[114:115], v[8:9], v[6:7] op_sel_hi:[0,1,1]
	v_pk_fma_f32 v[56:57], v[114:115], v[12:13], v[10:11] op_sel_hi:[0,1,1]
	v_pk_fma_f32 v[58:59], v[114:115], v[16:17], v[14:15] op_sel_hi:[0,1,1]
	v_pk_fma_f32 v[60:61], v[114:115], v[70:71], v[18:19] op_sel_hi:[0,1,1]
	v_pk_fma_f32 v[62:63], v[114:115], v[78:79], v[20:21] op_sel_hi:[0,1,1]
	v_pk_fma_f32 v[64:65], v[114:115], v[86:87], v[22:23] op_sel_hi:[0,1,1]
	v_pk_fma_f32 v[50:51], v[114:115], v[94:95], v[24:25] op_sel_hi:[0,1,1]
	ds_write2st64_b32 v40, v52, v53 offset1:1
	ds_write2st64_b32 v40, v54, v55 offset0:2 offset1:3
	ds_write2st64_b32 v40, v56, v57 offset0:4 offset1:5
	ds_write2st64_b32 v40, v58, v59 offset0:6 offset1:7
	ds_write2st64_b32 v40, v60, v61 offset0:8 offset1:9
	ds_write2st64_b32 v40, v62, v63 offset0:10 offset1:11
	ds_write2st64_b32 v40, v64, v65 offset0:12 offset1:13
	ds_write2st64_b32 v40, v50, v51 offset0:14 offset1:15
	s_waitcnt lgkmcnt(0)
	s_barrier
	s_and_saveexec_b64 s[2:3], vcc
	s_cbranch_execz .LBB0_31
	s_load_dwordx16 s[76:91], s[0:1], 0x0
	s_lshl_b32 s4, s8, 6
	v_or_b32_e32 v2, s4, v1
	v_ashrrev_i32_e32 v3, 31, v2
	s_ashr_i32 s5, s4, 31
	s_waitcnt lgkmcnt(0)
	v_lshl_add_u64 v[2:3], v[2:3], 2, s[82:83]
	v_lshl_add_u64 v[4:5], s[4:5], 2, v[42:43]
	s_mov_b64 s[6:7], 0
	v_mov_b32_e32 v6, v38
